# pass-3 without the one-time wave stagger; carry-in chain double-buffered
# baseline (speedup 1.0000x reference)
; DI void s5_pass3_item(const Params& P, int bitem, unsigned char* smem) {
;     ...
;     unsigned char* ws = P.ws; const int tid = tid_, wid = tid >> 6, lane = tid & 63, r = lane & 15, q = lane >> 4;
;     const int item = bitem * 8 + wid, ch = item & 31, grp = (item >> 5) & 63, b = item >> 11;
;     const bf16_t* proj = (const bf16_t*)(ws + WS_PROJ); const float* sm = (const float*)(ws + WS_SMALL);
;     float* xs = (float*)smem + wid * 2176;
;     bf16_t* HG = (bf16_t*)(ws + WS_HG);
;     const bf16_t* tb = (const bf16_t*)(sm + SM_BB);
;     bf16x8 af[8];
; #pragma unroll
;     for (int pt = 0; pt < 8; ++pt) af[pt] = *(const bf16x8*)(tb + (grp * 128 + 16 * pt + r) * 32 + 8 * q);
;     const f32x4 ab = *(const f32x4*)(sm + SM_AB + (grp * 64 + lane) * 4);
;     float cB[32];
;     { const float* cre = P.in[21] + (size_t)(grp * 16 + r) * 64; const float* cim = P.in[22] + (size_t)(grp * 16 + r) * 64;
; #pragma unroll
;       for (int i = 0; i < 32; ++i) { const int k = 4 * i + q; cB[i] = (i < 16) ? cre[k] : -cim[k - 64]; } }
;     const float dsk = P.in[23][grp * 16 + r];
;     const bf16_t* ubase = proj + (size_t)(b * TT + ch * 64) * NPROJ + C_SSM + grp * 16;
;     bf16x8 ubs[4]; unsigned short uvs[4][4];
; #pragma unroll
;     for (int sub = 0; sub < 4; ++sub) { ubs[sub] = *(const bf16x8*)(ubase + (size_t)(sub * 16 + r) * NPROJ + 8 * (q & 1));
; #pragma unroll
;         for (int j = 0; j < 4; ++j) uvs[sub][j] = ubase[(size_t)(sub * 16 + 4 * q + j) * NPROJ + r]; }
;     float xr = 0.f, xi = 0.f;
;     {
;       const f32x2_t* e = (const f32x2_t*)(ws + WS_S5END) + (size_t)((b * 64 + grp) * 32) * 64 + lane;
;       f32x2_t ev[31];
; #pragma unroll
;       for (int j = 0; j < 31; ++j) ev[j] = e[(j < ch ? j : 0) * 64];
.Ls5n_start:
	v_lshrrev_b32_e32 v1, 6, v206
	v_and_b32_e32 v2, 63, v206
	v_readfirstlane_b32 s16, v1
	v_and_b32_e32 v3, 15, v206
	v_bfe_u32 v4, v206, 4, 2
	s_lshr_b32 s17, s88, 2
	s_and_b32 s18, s88, 3
	s_lshl_b32 s18, s18, 3
	s_add_i32 s18, s18, s16
	v_mov_b32_e32 v205, 0
	s_mul_i32 s0, s16, 0x2200
	s_mov_b32 m0, s0
	v_mul_u32_u24_e32 v5, 0x210, v3
	v_lshl_add_u32 v5, v4, 4, v5
	v_add_u32_e32 v77, s0, v5
	v_lshlrev_b32_e32 v5, 2, v1
	v_add_u32_e32 v78, 0x19000, v5
	v_and_b32_e32 v5, 7, v2
	v_lshlrev_b32_e32 v5, 2, v5
	v_add_u32_e32 v79, 0x19000, v5
	v_lshlrev_b32_e32 v5, 3, v206
	v_add_u32_e32 v81, 0x11000, v5
	v_add_u32_e32 v199, 0x1000, v5
	v_add_u32_e32 v204, 0x3000, v5
	v_lshlrev_b32_e32 v5, 3, v2
	v_add_u32_e32 v82, 0x11000, v5
	v_and_b32_e32 v5, 1, v4
	v_lshlrev_b32_e32 v5, 4, v5
	s_movk_i32 s1, 0x1e00
	v_mad_u32_u24 v83, v3, s1, v5
	v_lshlrev_b32_e32 v5, 2, v4
	v_lshlrev_b32_e32 v6, 1, v3
	v_mad_u32_u24 v84, v5, s1, v6
	v_add_u32_e32 v85, 0x1e00, v84
	v_add_u32_e32 v86, 0x3c00, v84
	v_add_u32_e32 v87, 0x5a00, v84
	v_lshlrev_b32_e32 v7, 13, v4
	v_add_u32_e32 v7, v7, v6
	v_add_u32_e32 v198, 0x1000, v7
	s_lshl_b32 s2, s17, 13
	s_add_u32 s0, s74, 0x9f20400
	s_addc_u32 s1, s75, 0
	s_add_u32 s0, s0, s2
	s_addc_u32 s1, s1, 0
	s_add_u32 s2, s0, 0x1000
	s_addc_u32 s3, s1, 0
	v_lshlrev_b32_e32 v5, 6, v3
	v_lshl_add_u32 v5, v4, 4, v5
	global_load_dwordx4 v[8:11], v5, s[0:1] offset:0
	global_load_dwordx4 v[12:15], v5, s[0:1] offset:1024
	global_load_dwordx4 v[16:19], v5, s[0:1] offset:2048
	global_load_dwordx4 v[20:23], v5, s[0:1] offset:3072
	global_load_dwordx4 v[24:27], v5, s[2:3] offset:0
	global_load_dwordx4 v[28:31], v5, s[2:3] offset:1024
	global_load_dwordx4 v[32:35], v5, s[2:3] offset:2048
	global_load_dwordx4 v[36:39], v5, s[2:3] offset:3072
	s_lshl_b32 s6, s17, 10
	s_add_u32 s4, s74, 0x9f10400
	s_addc_u32 s5, s75, 0
	s_add_u32 s4, s4, s6
	s_addc_u32 s5, s5, 0
	v_lshlrev_b32_e32 v6, 4, v2
	global_load_dwordx4 v[72:75], v6, s[4:5]
	s_lshl_b32 s6, s17, 12
	s_add_u32 s8, s62, s6
	s_addc_u32 s9, s63, 0
	s_add_u32 s10, s64, s6
	s_addc_u32 s11, s65, 0
	v_lshlrev_b32_e32 v7, 8, v3
	v_lshl_add_u32 v7, v4, 4, v7
	global_load_dword v40, v7, s[8:9] offset:0
	global_load_dword v41, v7, s[8:9] offset:4
	global_load_dword v42, v7, s[8:9] offset:8
	global_load_dword v43, v7, s[8:9] offset:12
	global_load_dword v44, v7, s[8:9] offset:64
	global_load_dword v45, v7, s[8:9] offset:68
	global_load_dword v46, v7, s[8:9] offset:72
	global_load_dword v47, v7, s[8:9] offset:76
	global_load_dword v48, v7, s[8:9] offset:128
	global_load_dword v49, v7, s[8:9] offset:132
	global_load_dword v50, v7, s[8:9] offset:136
	global_load_dword v51, v7, s[8:9] offset:140
	global_load_dword v52, v7, s[8:9] offset:192
	global_load_dword v53, v7, s[8:9] offset:196
	global_load_dword v54, v7, s[8:9] offset:200
	global_load_dword v55, v7, s[8:9] offset:204
	global_load_dword v56, v7, s[10:11] offset:0
	global_load_dword v57, v7, s[10:11] offset:4
	global_load_dword v58, v7, s[10:11] offset:8
	global_load_dword v59, v7, s[10:11] offset:12
	global_load_dword v60, v7, s[10:11] offset:64
	global_load_dword v61, v7, s[10:11] offset:68
	global_load_dword v62, v7, s[10:11] offset:72
	global_load_dword v63, v7, s[10:11] offset:76
	global_load_dword v64, v7, s[10:11] offset:128
	global_load_dword v65, v7, s[10:11] offset:132
	global_load_dword v66, v7, s[10:11] offset:136
	global_load_dword v67, v7, s[10:11] offset:140
	global_load_dword v68, v7, s[10:11] offset:192
	global_load_dword v69, v7, s[10:11] offset:196
	global_load_dword v70, v7, s[10:11] offset:200
	global_load_dword v71, v7, s[10:11] offset:204
	s_lshl_b32 s6, s17, 6
	s_add_u32 s12, s66, s6
	s_addc_u32 s13, s67, 0
	v_lshlrev_b32_e32 v6, 2, v3
	global_load_dword v76, v6, s[12:13]
	s_mul_i32 s0, s18, 0x78000
	s_lshl_b32 s1, s17, 5
	s_add_i32 s0, s0, s1
	s_add_i32 s0, s0, 0xf911430
	s_add_u32 s22, s74, s0
	s_addc_u32 s23, s75, 0
	s_lshl_b32 s0, s17, 14
	s_add_i32 s0, s0, 0xa110000
	s_add_u32 s24, s74, s0
	s_addc_u32 s25, s75, 0
	s_lshl_b32 s0, s18, 17
	s_lshl_b32 s1, s17, 5
	s_add_i32 s0, s0, s1
	s_add_i32 s0, s0, 0xb910000
	s_add_u32 s26, s74, s0
	s_addc_u32 s27, s75, 0
	s_add_u32 s40, s22, 0x0
	s_addc_u32 s41, s23, 0
	s_add_u32 s42, s22, 0x1e000
	s_addc_u32 s43, s23, 0
	s_add_u32 s44, s22, 0x3c000
	s_addc_u32 s45, s23, 0
	s_add_u32 s46, s22, 0x5a000
	s_addc_u32 s47, s23, 0
	global_load_dwordx4 v[120:123], v83, s[40:41]
	global_load_dwordx4 v[124:127], v83, s[42:43]
	global_load_dwordx4 v[128:131], v83, s[44:45]
	global_load_dwordx4 v[132:135], v83, s[46:47]
	global_load_ushort v136, v84, s[40:41]
	global_load_ushort v137, v85, s[40:41]
	global_load_ushort v138, v86, s[40:41]
	global_load_ushort v139, v87, s[40:41]
	global_load_ushort v140, v84, s[42:43]
	global_load_ushort v141, v85, s[42:43]
	global_load_ushort v142, v86, s[42:43]
	global_load_ushort v143, v87, s[42:43]
	global_load_ushort v144, v84, s[44:45]
	global_load_ushort v145, v85, s[44:45]
	global_load_ushort v146, v86, s[44:45]
	global_load_ushort v147, v87, s[44:45]
	global_load_ushort v148, v84, s[46:47]
	global_load_ushort v149, v85, s[46:47]
	global_load_ushort v150, v86, s[46:47]
	global_load_ushort v151, v87, s[46:47]
	global_load_dwordx2 v[152:153], v199, s[24:25] offset:-4096
	global_load_dwordx2 v[154:155], v199, s[24:25]
	global_load_dwordx2 v[156:157], v204, s[24:25] offset:-4096
	global_load_dwordx2 v[158:159], v204, s[24:25]
	s_mov_b32 s19, 0
	s_mov_b32 s20, 0
	s_waitcnt vmcnt(0)
	v_xor_b32_e32 v56, 0x80000000, v56
	v_xor_b32_e32 v57, 0x80000000, v57
	v_xor_b32_e32 v58, 0x80000000, v58
	v_xor_b32_e32 v59, 0x80000000, v59
	v_xor_b32_e32 v60, 0x80000000, v60
	v_xor_b32_e32 v61, 0x80000000, v61
	v_xor_b32_e32 v62, 0x80000000, v62
	v_xor_b32_e32 v63, 0x80000000, v63
	v_xor_b32_e32 v64, 0x80000000, v64
	v_xor_b32_e32 v65, 0x80000000, v65
	v_xor_b32_e32 v66, 0x80000000, v66
	v_xor_b32_e32 v67, 0x80000000, v67
	v_xor_b32_e32 v68, 0x80000000, v68
	v_xor_b32_e32 v69, 0x80000000, v69
	v_xor_b32_e32 v70, 0x80000000, v70
	v_xor_b32_e32 v71, 0x80000000, v71
	ds_write_b64 v81, v[152:153] offset:0
	ds_write_b64 v81, v[154:155] offset:4096
	ds_write_b64 v81, v[156:157] offset:8192
	ds_write_b64 v81, v[158:159] offset:12288
	v_mov_b32_e32 v1, 1
	s_waitcnt lgkmcnt(0)
	ds_write_b32 v78, v1
	s_waitcnt lgkmcnt(0)
	s_barrier
; DI float bf2f(unsigned x) { return __uint_as_float(x << 16); }
; DI void s5_pass3_item(const Params& P, int bitem, unsigned char* smem) {
;     ...
; #pragma unroll
;     for (int sub = 0; sub < 4; ++sub) { ubs[sub] = *(const bf16x8*)(ubase + (size_t)(sub * 16 + r) * NPROJ + 8 * (q & 1));
; #pragma unroll
;         for (int j = 0; j < 4; ++j) uvs[sub][j] = ubase[(size_t)(sub * 16 + 4 * q + j) * NPROJ + r]; }
;     float xr = 0.f, xi = 0.f;
;     {
;       const f32x2_t* e = (const f32x2_t*)(ws + WS_S5END) + (size_t)((b * 64 + grp) * 32) * 64 + lane;
;       f32x2_t ev[31];
; #pragma unroll
;       for (int j = 0; j < 31; ++j) ev[j] = e[(j < ch ? j : 0) * 64];
; #pragma unroll
;       for (int j = 0; j < 31; ++j) { const float ex = j < ch ? ev[j][0] : 0.f, ey = j < ch ? ev[j][1] : 0.f;
;           const float ncr = ab[2] * xr - ab[3] * xi + ex, nci = ab[2] * xi + ab[3] * xr + ey; xr = j < ch ? ncr : xr; xi = j < ch ? nci : xi; } }
; #pragma unroll
;     for (int sub = 0; sub < 4; ++sub) {
;         s5_bu16(ubs[sub], af, xs, r, q);
;         float uv[4];
; #pragma unroll
;         for (int j = 0; j < 4; ++j) uv[j] = bf2f(uvs[sub][j]);
.Ls5n_round:
	s_waitcnt vmcnt(16)
	v_mov_b32_e32 v88, v120
	v_mov_b32_e32 v89, v121
	v_mov_b32_e32 v90, v122
	v_mov_b32_e32 v91, v123
	v_mov_b32_e32 v92, v124
	v_mov_b32_e32 v93, v125
	v_mov_b32_e32 v94, v126
	v_mov_b32_e32 v95, v127
	v_mov_b32_e32 v96, v128
	v_mov_b32_e32 v97, v129
	v_mov_b32_e32 v98, v130
	v_mov_b32_e32 v99, v131
	v_mov_b32_e32 v100, v132
	v_mov_b32_e32 v101, v133
	v_mov_b32_e32 v102, v134
	v_mov_b32_e32 v103, v135
	v_lshlrev_b32_e32 v104, 16, v136
	v_lshlrev_b32_e32 v105, 16, v137
	v_lshlrev_b32_e32 v106, 16, v138
	v_lshlrev_b32_e32 v107, 16, v139
	v_lshlrev_b32_e32 v108, 16, v140
	v_lshlrev_b32_e32 v109, 16, v141
	v_lshlrev_b32_e32 v110, 16, v142
	v_lshlrev_b32_e32 v111, 16, v143
	v_lshlrev_b32_e32 v112, 16, v144
	v_lshlrev_b32_e32 v113, 16, v145
	v_lshlrev_b32_e32 v114, 16, v146
	v_lshlrev_b32_e32 v115, 16, v147
	v_lshlrev_b32_e32 v116, 16, v148
	v_lshlrev_b32_e32 v117, 16, v149
	v_lshlrev_b32_e32 v118, 16, v150
	v_lshlrev_b32_e32 v119, 16, v151
	v_mov_b32_e32 v2, s19

; DI void s5_pass3_item(const Params& P, int bitem, unsigned char* smem) {
;     ...
;     {
;       const f32x2_t* e = (const f32x2_t*)(ws + WS_S5END) + (size_t)((b * 64 + grp) * 32) * 64 + lane;
;       f32x2_t ev[31];
; #pragma unroll
;       for (int j = 0; j < 31; ++j) ev[j] = e[(j < ch ? j : 0) * 64];
; #pragma unroll
;       for (int j = 0; j < 31; ++j) { const float ex = j < ch ? ev[j][0] : 0.f, ey = j < ch ? ev[j][1] : 0.f;
;           const float ncr = ab[2] * xr - ab[3] * xi + ex, nci = ab[2] * xi + ab[3] * xr + ey; xr = j < ch ? ncr : xr; xi = j < ch ? nci : xi; } }
.Ls5n_nopf:
	v_mov_b32_e32 v192, 0
	v_mov_b32_e32 v193, 0
	v_add_u32_e32 v1, s20, v82
	s_mov_b32 s30, 0
	s_cmp_ge_u32 s30, s18
	s_cbranch_scc1 .Ls5n_cdone
	ds_read_b64 v[2:3], v1 offset:0
	ds_read_b64 v[4:5], v1 offset:512
	ds_read_b64 v[6:7], v1 offset:1024
	ds_read_b64 v[246:247], v1 offset:1536
.Ls5n_cloop:
	ds_read_b64 v[208:209], v1 offset:2048
	ds_read_b64 v[210:211], v1 offset:2560
	ds_read_b64 v[212:213], v1 offset:3072
	ds_read_b64 v[214:215], v1 offset:3584
	v_add_u32_e32 v1, 0x800, v1
	s_waitcnt lgkmcnt(7)
	v_mul_f32_e32 v194, v75, v193
	v_mul_f32_e32 v195, v75, v192
	v_fma_f32 v194, v74, v192, -v194
	v_fma_f32 v195, v74, v193, v195
	v_add_f32_e32 v192, v194, v2
	v_add_f32_e32 v193, v195, v3
	s_add_i32 s30, s30, 1
	s_cmp_ge_u32 s30, s18
	s_cbranch_scc1 .Ls5n_cdone
	s_waitcnt lgkmcnt(6)
	v_mul_f32_e32 v194, v75, v193
	v_mul_f32_e32 v195, v75, v192
	v_fma_f32 v194, v74, v192, -v194
	v_fma_f32 v195, v74, v193, v195
	v_add_f32_e32 v192, v194, v4
	v_add_f32_e32 v193, v195, v5
	s_add_i32 s30, s30, 1
	s_cmp_ge_u32 s30, s18
	s_cbranch_scc1 .Ls5n_cdone
	s_waitcnt lgkmcnt(5)
	v_mul_f32_e32 v194, v75, v193
	v_mul_f32_e32 v195, v75, v192
	v_fma_f32 v194, v74, v192, -v194
	v_fma_f32 v195, v74, v193, v195
	v_add_f32_e32 v192, v194, v6
	v_add_f32_e32 v193, v195, v7
	s_add_i32 s30, s30, 1
	s_cmp_ge_u32 s30, s18
	s_cbranch_scc1 .Ls5n_cdone
	s_waitcnt lgkmcnt(4)
	v_mul_f32_e32 v194, v75, v193
	v_mul_f32_e32 v195, v75, v192
	v_fma_f32 v194, v74, v192, -v194
	v_fma_f32 v195, v74, v193, v195
	v_add_f32_e32 v192, v194, v246
	v_add_f32_e32 v193, v195, v247
	s_add_i32 s30, s30, 1
	s_cmp_ge_u32 s30, s18
	s_cbranch_scc1 .Ls5n_cdone
	ds_read_b64 v[2:3], v1 offset:2048
	ds_read_b64 v[4:5], v1 offset:2560
	ds_read_b64 v[6:7], v1 offset:3072
	ds_read_b64 v[246:247], v1 offset:3584
	v_add_u32_e32 v1, 0x800, v1
	s_waitcnt lgkmcnt(7)
	v_mul_f32_e32 v194, v75, v193
	v_mul_f32_e32 v195, v75, v192
	v_fma_f32 v194, v74, v192, -v194
	v_fma_f32 v195, v74, v193, v195
	v_add_f32_e32 v192, v194, v208
	v_add_f32_e32 v193, v195, v209
	s_add_i32 s30, s30, 1
	s_cmp_ge_u32 s30, s18
	s_cbranch_scc1 .Ls5n_cdone
	s_waitcnt lgkmcnt(6)
	v_mul_f32_e32 v194, v75, v193
	v_mul_f32_e32 v195, v75, v192
	v_fma_f32 v194, v74, v192, -v194
	v_fma_f32 v195, v74, v193, v195
	v_add_f32_e32 v192, v194, v210
	v_add_f32_e32 v193, v195, v211
	s_add_i32 s30, s30, 1
	s_cmp_ge_u32 s30, s18
	s_cbranch_scc1 .Ls5n_cdone
	s_waitcnt lgkmcnt(5)
	v_mul_f32_e32 v194, v75, v193
	v_mul_f32_e32 v195, v75, v192
	v_fma_f32 v194, v74, v192, -v194
	v_fma_f32 v195, v74, v193, v195
	v_add_f32_e32 v192, v194, v212
	v_add_f32_e32 v193, v195, v213
	s_add_i32 s30, s30, 1
	s_cmp_ge_u32 s30, s18
	s_cbranch_scc1 .Ls5n_cdone
	s_waitcnt lgkmcnt(4)
	v_mul_f32_e32 v194, v75, v193
	v_mul_f32_e32 v195, v75, v192
	v_fma_f32 v194, v74, v192, -v194
	v_fma_f32 v195, v74, v193, v195
	v_add_f32_e32 v192, v194, v214
	v_add_f32_e32 v193, v195, v215
	s_add_i32 s30, s30, 1
	s_cmp_ge_u32 s30, s18
	s_cbranch_scc1 .Ls5n_cdone
	s_branch .Ls5n_cloop
